# prompt attention: software-pipelined path for unmasked 128-key tiles (QK of 2nd half overlaps exp of 1st, PV overlaps exp/cvt)
# speedup vs baseline: 1.0212x; 1.0051x over previous
.LBB0_1554:
	s_lshl_b32 s44, s12, 1
	v_add_u32_e32 v240, s0, v203
	v_add_u32_e32 v241, s1, v204
	s_or_b32 s45, s44, 1
	s_cmp_lt_u32 s45, s43
	s_cbranch_scc1 .Lmy_pa1_full
	s_mov_b32 s45, 0
	s_mov_b64 s[0:1], -1
	s_branch .LBB0_1557

.Lmy_pa1_full:
	v_mad_u32_u24 v184, v124, s28, v240
	v_add_u32_e32 v185, 0x2400, v241
	ds_read_b128 v[186:189], v184
	ds_read_b128 v[242:245], v184 offset:6656
	ds_read_b128 v[246:249], v184 offset:32
	ds_read_b128 v[250:253], v184 offset:6688
	ds_read_b128 v[176:179], v184 offset:64
	ds_read_b128 v[180:183], v184 offset:6720
	s_waitcnt lgkmcnt(5)
	v_mfma_f32_32x32x16_bf16 v[48:63], v[186:189], v[84:87], v[0:15]
	ds_read_b128 v[186:189], v184 offset:96
	s_waitcnt lgkmcnt(5)
	v_mfma_f32_32x32x16_bf16 v[64:79], v[242:245], v[84:87], v[0:15]
	ds_read_b128 v[242:245], v184 offset:6752
	s_waitcnt lgkmcnt(5)
	v_mfma_f32_32x32x16_bf16 v[48:63], v[246:249], v[88:91], v[48:63]
	ds_read_b128 v[246:249], v184 offset:128
	s_waitcnt lgkmcnt(5)
	v_mfma_f32_32x32x16_bf16 v[64:79], v[250:253], v[88:91], v[64:79]
	ds_read_b128 v[250:253], v184 offset:6784
	s_waitcnt lgkmcnt(5)
	v_mfma_f32_32x32x16_bf16 v[48:63], v[176:179], v[92:95], v[48:63]
	ds_read_b128 v[176:179], v184 offset:160
	s_waitcnt lgkmcnt(5)
	v_mfma_f32_32x32x16_bf16 v[64:79], v[180:183], v[92:95], v[64:79]
	ds_read_b128 v[180:183], v184 offset:6816
	s_waitcnt lgkmcnt(5)
	v_mfma_f32_32x32x16_bf16 v[48:63], v[186:189], v[96:99], v[48:63]
	ds_read_b128 v[186:189], v184 offset:13312
	s_waitcnt lgkmcnt(5)
	v_mfma_f32_32x32x16_bf16 v[64:79], v[242:245], v[96:99], v[64:79]
	ds_read_b128 v[242:245], v184 offset:19968
	s_waitcnt lgkmcnt(5)
	v_mfma_f32_32x32x16_bf16 v[48:63], v[246:249], v[100:103], v[48:63]
	ds_read_b128 v[246:249], v184 offset:13344
	s_waitcnt lgkmcnt(5)
	v_mfma_f32_32x32x16_bf16 v[64:79], v[250:253], v[100:103], v[64:79]
	ds_read_b128 v[250:253], v184 offset:20000
	s_waitcnt lgkmcnt(5)
	v_mfma_f32_32x32x16_bf16 v[48:63], v[176:179], v[112:115], v[48:63]
	ds_read_b128 v[176:179], v184 offset:13376
	s_waitcnt lgkmcnt(5)
	v_mfma_f32_32x32x16_bf16 v[64:79], v[180:183], v[112:115], v[64:79]
	ds_read_b128 v[180:183], v184 offset:20032
	s_waitcnt lgkmcnt(5)
	v_mfma_f32_32x32x16_bf16 v[144:159], v[186:189], v[84:87], v[0:15]
	ds_read_b128 v[186:189], v184 offset:13408
	s_waitcnt lgkmcnt(5)
	v_mfma_f32_32x32x16_bf16 v[160:175], v[242:245], v[84:87], v[0:15]
	ds_read_b128 v[242:245], v184 offset:20064
	s_nop 4
	v_exp_f32_e32 v48, v48
	v_exp_f32_e32 v49, v49
	v_exp_f32_e32 v50, v50
	s_waitcnt lgkmcnt(5)
	v_mfma_f32_32x32x16_bf16 v[144:159], v[246:249], v[88:91], v[144:159]
	ds_read_b128 v[246:249], v184 offset:13440
	v_exp_f32_e32 v51, v51
	v_exp_f32_e32 v52, v52
	v_exp_f32_e32 v53, v53
	s_waitcnt lgkmcnt(5)
	v_mfma_f32_32x32x16_bf16 v[160:175], v[250:253], v[88:91], v[160:175]
	ds_read_b128 v[250:253], v184 offset:20096
	v_exp_f32_e32 v54, v54
	v_exp_f32_e32 v55, v55
	v_exp_f32_e32 v56, v56
	s_waitcnt lgkmcnt(5)
	v_mfma_f32_32x32x16_bf16 v[144:159], v[176:179], v[92:95], v[144:159]
	ds_read_b128 v[176:179], v184 offset:13472
	v_exp_f32_e32 v57, v57
	v_exp_f32_e32 v58, v58
	v_exp_f32_e32 v59, v59
	s_waitcnt lgkmcnt(5)
	v_mfma_f32_32x32x16_bf16 v[160:175], v[180:183], v[92:95], v[160:175]
	ds_read_b128 v[180:183], v184 offset:20128
	v_exp_f32_e32 v60, v60
	v_exp_f32_e32 v61, v61
	v_exp_f32_e32 v62, v62
	s_waitcnt lgkmcnt(5)
	v_mfma_f32_32x32x16_bf16 v[144:159], v[186:189], v[96:99], v[144:159]
	ds_read_b64_tr_b16 v[186:187], v241 offset:53248
	ds_read_b64_tr_b16 v[188:189], v241 offset:54400
	v_exp_f32_e32 v63, v63
	v_exp_f32_e32 v64, v64
	v_exp_f32_e32 v65, v65
	s_waitcnt lgkmcnt(6)
	v_mfma_f32_32x32x16_bf16 v[160:175], v[242:245], v[96:99], v[160:175]
	ds_read_b64_tr_b16 v[242:243], v241 offset:53312
	ds_read_b64_tr_b16 v[244:245], v241 offset:54464
	v_exp_f32_e32 v66, v66
	v_exp_f32_e32 v67, v67
	v_exp_f32_e32 v68, v68
	s_waitcnt lgkmcnt(7)
	v_mfma_f32_32x32x16_bf16 v[144:159], v[246:249], v[100:103], v[144:159]
	ds_read_b64_tr_b16 v[246:247], v241 offset:55552
	ds_read_b64_tr_b16 v[248:249], v241 offset:56704
	v_exp_f32_e32 v69, v69
	v_exp_f32_e32 v70, v70
	v_exp_f32_e32 v71, v71
	s_waitcnt lgkmcnt(8)
	v_mfma_f32_32x32x16_bf16 v[160:175], v[250:253], v[100:103], v[160:175]
	ds_read_b64_tr_b16 v[250:251], v241 offset:55616
	ds_read_b64_tr_b16 v[252:253], v241 offset:56768
	v_exp_f32_e32 v72, v72
	v_exp_f32_e32 v73, v73
	v_exp_f32_e32 v74, v74
	s_waitcnt lgkmcnt(9)
	v_mfma_f32_32x32x16_bf16 v[144:159], v[176:179], v[112:115], v[144:159]
	v_cvt_pk_bf16_f32 v176, v48, v49
	v_cvt_pk_bf16_f32 v177, v50, v51
	v_cvt_pk_bf16_f32 v178, v52, v53
	v_cvt_pk_bf16_f32 v179, v54, v55
	v_exp_f32_e32 v75, v75
	s_waitcnt lgkmcnt(8)
	v_mfma_f32_32x32x16_bf16 v[160:175], v[180:183], v[112:115], v[160:175]
	v_exp_f32_e32 v76, v76
	v_exp_f32_e32 v77, v77
	v_exp_f32_e32 v78, v78
	s_waitcnt lgkmcnt(6)
	v_mfma_f32_32x32x16_bf16 v[16:31], v[176:179], v[186:189], v[16:31]
	ds_read_b64_tr_b16 v[186:187], v241 offset:57856
	ds_read_b64_tr_b16 v[188:189], v241 offset:59008
	v_cvt_pk_bf16_f32 v180, v56, v57
	v_cvt_pk_bf16_f32 v181, v58, v59
	v_cvt_pk_bf16_f32 v182, v60, v61
	v_cvt_pk_bf16_f32 v183, v62, v63
	v_exp_f32_e32 v79, v79
	v_exp_f32_e32 v144, v144
	s_waitcnt lgkmcnt(6)
	v_mfma_f32_32x32x16_bf16 v[32:47], v[176:179], v[242:245], v[32:47]
	ds_read_b64_tr_b16 v[242:243], v241 offset:57920
	ds_read_b64_tr_b16 v[244:245], v241 offset:59072
	v_cvt_pk_bf16_f32 v176, v64, v65
	v_cvt_pk_bf16_f32 v177, v66, v67
	v_cvt_pk_bf16_f32 v178, v68, v69
	v_cvt_pk_bf16_f32 v179, v70, v71
	v_exp_f32_e32 v145, v145
	v_exp_f32_e32 v146, v146
	s_waitcnt lgkmcnt(6)
	v_mfma_f32_32x32x16_bf16 v[16:31], v[180:183], v[246:249], v[16:31]
	ds_read_b64_tr_b16 v[246:247], v241 offset:60160
	ds_read_b64_tr_b16 v[248:249], v241 offset:61312
	v_exp_f32_e32 v147, v147
	v_exp_f32_e32 v148, v148
	v_exp_f32_e32 v149, v149
	v_exp_f32_e32 v150, v150
	s_waitcnt lgkmcnt(6)
	v_mfma_f32_32x32x16_bf16 v[32:47], v[180:183], v[250:253], v[32:47]
	ds_read_b64_tr_b16 v[250:251], v241 offset:60224
	ds_read_b64_tr_b16 v[252:253], v241 offset:61376
	v_cvt_pk_bf16_f32 v180, v72, v73
	v_cvt_pk_bf16_f32 v181, v74, v75
	v_cvt_pk_bf16_f32 v182, v76, v77
	v_cvt_pk_bf16_f32 v183, v78, v79
	v_exp_f32_e32 v151, v151
	v_exp_f32_e32 v152, v152
	s_waitcnt lgkmcnt(6)
	v_mfma_f32_32x32x16_bf16 v[16:31], v[176:179], v[186:189], v[16:31]
	ds_read_b64_tr_b16 v[186:187], v185 offset:53248
	ds_read_b64_tr_b16 v[188:189], v185 offset:54400
	v_exp_f32_e32 v153, v153
	v_exp_f32_e32 v154, v154
	v_exp_f32_e32 v155, v155
	v_exp_f32_e32 v156, v156
	s_waitcnt lgkmcnt(6)
	v_mfma_f32_32x32x16_bf16 v[32:47], v[176:179], v[242:245], v[32:47]
	ds_read_b64_tr_b16 v[242:243], v185 offset:53312
	ds_read_b64_tr_b16 v[244:245], v185 offset:54464
	v_cvt_pk_bf16_f32 v176, v144, v145
	v_cvt_pk_bf16_f32 v177, v146, v147
	v_cvt_pk_bf16_f32 v178, v148, v149
	v_cvt_pk_bf16_f32 v179, v150, v151
	v_exp_f32_e32 v157, v157
	v_exp_f32_e32 v158, v158
	s_waitcnt lgkmcnt(6)
	v_mfma_f32_32x32x16_bf16 v[16:31], v[180:183], v[246:249], v[16:31]
	ds_read_b64_tr_b16 v[246:247], v185 offset:55552
	ds_read_b64_tr_b16 v[248:249], v185 offset:56704
	v_exp_f32_e32 v159, v159
	v_exp_f32_e32 v160, v160
	v_exp_f32_e32 v161, v161
	v_exp_f32_e32 v162, v162
	s_waitcnt lgkmcnt(6)
	v_mfma_f32_32x32x16_bf16 v[32:47], v[180:183], v[250:253], v[32:47]
	ds_read_b64_tr_b16 v[250:251], v185 offset:55616
	ds_read_b64_tr_b16 v[252:253], v185 offset:56768
	v_cvt_pk_bf16_f32 v180, v152, v153
	v_cvt_pk_bf16_f32 v181, v154, v155
	v_cvt_pk_bf16_f32 v182, v156, v157
	v_cvt_pk_bf16_f32 v183, v158, v159
	v_exp_f32_e32 v163, v163
	v_exp_f32_e32 v164, v164
	s_waitcnt lgkmcnt(6)
	v_mfma_f32_32x32x16_bf16 v[16:31], v[176:179], v[186:189], v[16:31]
	ds_read_b64_tr_b16 v[186:187], v185 offset:57856
	ds_read_b64_tr_b16 v[188:189], v185 offset:59008
	v_exp_f32_e32 v165, v165
	v_exp_f32_e32 v166, v166
	v_exp_f32_e32 v167, v167
	v_exp_f32_e32 v168, v168
	s_waitcnt lgkmcnt(6)
	v_mfma_f32_32x32x16_bf16 v[32:47], v[176:179], v[242:245], v[32:47]
	ds_read_b64_tr_b16 v[242:243], v185 offset:57920
	ds_read_b64_tr_b16 v[244:245], v185 offset:59072
	v_cvt_pk_bf16_f32 v176, v160, v161
	v_cvt_pk_bf16_f32 v177, v162, v163
	v_cvt_pk_bf16_f32 v178, v164, v165
	v_cvt_pk_bf16_f32 v179, v166, v167
	v_exp_f32_e32 v169, v169
	v_exp_f32_e32 v170, v170
	s_waitcnt lgkmcnt(6)
	v_mfma_f32_32x32x16_bf16 v[16:31], v[180:183], v[246:249], v[16:31]
	ds_read_b64_tr_b16 v[246:247], v185 offset:60160
	ds_read_b64_tr_b16 v[248:249], v185 offset:61312
	v_exp_f32_e32 v171, v171
	v_exp_f32_e32 v172, v172
	v_exp_f32_e32 v173, v173
	v_exp_f32_e32 v174, v174
	s_waitcnt lgkmcnt(6)
	v_mfma_f32_32x32x16_bf16 v[32:47], v[180:183], v[250:253], v[32:47]
	ds_read_b64_tr_b16 v[250:251], v185 offset:60224
	ds_read_b64_tr_b16 v[252:253], v185 offset:61376
	v_exp_f32_e32 v175, v175
	v_cvt_pk_bf16_f32 v180, v168, v169
	v_cvt_pk_bf16_f32 v181, v170, v171
	v_cvt_pk_bf16_f32 v182, v172, v173
	v_cvt_pk_bf16_f32 v183, v174, v175
	v_add_f32_e32 v184, v48, v64
	v_add_f32_e32 v184, v184, v49
	s_waitcnt lgkmcnt(6)
	v_mfma_f32_32x32x16_bf16 v[16:31], v[176:179], v[186:189], v[16:31]
	v_add_f32_e32 v184, v184, v65
	v_add_f32_e32 v184, v184, v50
	v_add_f32_e32 v184, v184, v66
	v_add_f32_e32 v184, v184, v51
	v_add_f32_e32 v184, v184, v67
	v_add_f32_e32 v184, v184, v52
	v_add_f32_e32 v184, v184, v68
	v_add_f32_e32 v184, v184, v53
	s_waitcnt lgkmcnt(4)
	v_mfma_f32_32x32x16_bf16 v[32:47], v[176:179], v[242:245], v[32:47]
	v_add_f32_e32 v184, v184, v69
	v_add_f32_e32 v184, v184, v54
	v_add_f32_e32 v184, v184, v70
	v_add_f32_e32 v184, v184, v55
	v_add_f32_e32 v184, v184, v71
	v_add_f32_e32 v184, v184, v56
	v_add_f32_e32 v184, v184, v72
	v_add_f32_e32 v184, v184, v57
	s_waitcnt lgkmcnt(2)
	v_mfma_f32_32x32x16_bf16 v[16:31], v[180:183], v[246:249], v[16:31]
	v_add_f32_e32 v184, v184, v73
	v_add_f32_e32 v184, v184, v58
	v_add_f32_e32 v184, v184, v74
	v_add_f32_e32 v184, v184, v59
	v_add_f32_e32 v184, v184, v75
	v_add_f32_e32 v184, v184, v60
	v_add_f32_e32 v184, v184, v76
	v_add_f32_e32 v184, v184, v61
	s_waitcnt lgkmcnt(0)
	v_mfma_f32_32x32x16_bf16 v[32:47], v[180:183], v[250:253], v[32:47]
	v_add_f32_e32 v184, v184, v77
	v_add_f32_e32 v184, v184, v62
	v_add_f32_e32 v184, v184, v78
	v_add_f32_e32 v184, v184, v63
	v_add_f32_e32 v184, v184, v79
	v_add_f32_e32 v184, v184, v144
	v_add_f32_e32 v184, v184, v160
	v_add_f32_e32 v184, v184, v145
	v_add_f32_e32 v184, v184, v161
	v_add_f32_e32 v184, v184, v146
	v_add_f32_e32 v184, v184, v162
	v_add_f32_e32 v184, v184, v147
	v_add_f32_e32 v184, v184, v163
	v_add_f32_e32 v184, v184, v148
	v_add_f32_e32 v184, v184, v164
	v_add_f32_e32 v184, v184, v149
	v_add_f32_e32 v184, v184, v165
	v_add_f32_e32 v184, v184, v150
	v_add_f32_e32 v184, v184, v166
	v_add_f32_e32 v184, v184, v151
	v_add_f32_e32 v184, v184, v167
	v_add_f32_e32 v184, v184, v152
	v_add_f32_e32 v184, v184, v168
	v_add_f32_e32 v184, v184, v153
	v_add_f32_e32 v184, v184, v169
	v_add_f32_e32 v184, v184, v154
	v_add_f32_e32 v184, v184, v170
	v_add_f32_e32 v184, v184, v155
	v_add_f32_e32 v184, v184, v171
	v_add_f32_e32 v184, v184, v156
	v_add_f32_e32 v184, v184, v172
	v_add_f32_e32 v184, v184, v157
	v_add_f32_e32 v184, v184, v173
	v_add_f32_e32 v184, v184, v158
	v_add_f32_e32 v184, v184, v174
	v_add_f32_e32 v184, v184, v159
	v_add_f32_e32 v184, v184, v175
	v_add_f32_e32 v239, v239, v184

.LBB0_1562:
	v_lshlrev_b32_e32 v144, 10, v142
	v_mov_b32_e32 v145, 0
	v_or_b32_e32 v146, 1, v142
	v_lshlrev_b32_e32 v146, 10, v146
	v_mov_b32_e32 v147, 0
	v_or_b32_e32 v148, 2, v142
	v_lshlrev_b32_e32 v148, 10, v148
	v_mov_b32_e32 v149, 0
	v_or_b32_e32 v150, 3, v142
	v_lshlrev_b32_e32 v150, 10, v150
	v_mov_b32_e32 v151, 0
	v_add_u32_e32 v152, 0x2000, v144
	v_mov_b32_e32 v153, 0
	v_add_u32_e32 v154, 0x2400, v144
	v_mov_b32_e32 v155, 0
	v_add_u32_e32 v156, 0x2800, v144
	v_mov_b32_e32 v157, 0
	v_add_u32_e32 v158, 0x2c00, v144
	v_mov_b32_e32 v159, 0
	v_add_u32_e32 v160, 0x4000, v144
	v_mov_b32_e32 v161, 0
	v_add_u32_e32 v162, 0x4400, v144
	v_mov_b32_e32 v163, 0
	v_add_u32_e32 v164, 0x4800, v144
	v_mov_b32_e32 v165, 0
	v_add_u32_e32 v166, 0x4c00, v144
	v_mov_b32_e32 v167, 0
	v_add_u32_e32 v168, 0x6000, v144
	v_mov_b32_e32 v169, 0
	v_add_u32_e32 v170, 0x6400, v144
	v_mov_b32_e32 v171, 0
	v_add_u32_e32 v172, 0x6800, v144
	v_mov_b32_e32 v173, 0
	v_add_u32_e32 v174, 0x6c00, v144
	v_mov_b32_e32 v175, 0
	v_lshl_add_u64 v[176:177], v[140:141], 1, s[18:19]
	v_lshl_add_u64 v[178:179], v[132:133], 1, s[16:17]
	v_lshl_add_u64 v[182:183], v[136:137], 1, s[16:17]
	v_lshl_add_u64 v[180:181], v[134:135], 1, s[16:17]
	v_lshl_add_u64 v[184:185], v[138:139], 1, s[18:19]
	ds_bpermute_b32 v48, v199, v239
	s_and_saveexec_b64 s[0:1], s[2:3]
	s_cbranch_execz .LBB0_1564
	s_waitcnt lgkmcnt(0)
	v_add_f32_e32 v48, v239, v48
	ds_write_b32 v206, v48

.LBB0_1567:
	s_lshl_b32 s39, s0, 1
	v_add_u32_e32 v230, s1, v203
	v_add_u32_e32 v231, s12, v204
	s_or_b32 s40, s39, 1
	s_cmp_lt_u32 s40, s38
	s_cbranch_scc1 .Lmy_pa2_full
	s_mov_b32 s40, 0
	s_mov_b64 s[0:1], -1
	s_branch .LBB0_1570

.Lmy_pa2_full:
	v_mad_u32_u24 v252, v124, s28, v230
	v_add_u32_e32 v253, 0x2400, v231
	ds_read_b128 v[176:179], v252
	ds_read_b128 v[232:235], v252 offset:6656
	ds_read_b128 v[236:239], v252 offset:32
	ds_read_b128 v[240:243], v252 offset:6688
	ds_read_b128 v[244:247], v252 offset:64
	ds_read_b128 v[248:251], v252 offset:6720
	s_waitcnt lgkmcnt(5)
	v_mfma_f32_32x32x16_bf16 v[48:63], v[176:179], v[80:83], v[0:15]
	ds_read_b128 v[176:179], v252 offset:96
	s_waitcnt lgkmcnt(5)
	v_mfma_f32_32x32x16_bf16 v[64:79], v[232:235], v[80:83], v[0:15]
	ds_read_b128 v[232:235], v252 offset:6752
	s_waitcnt lgkmcnt(5)
	v_mfma_f32_32x32x16_bf16 v[48:63], v[236:239], v[88:91], v[48:63]
	ds_read_b128 v[236:239], v252 offset:128
	s_waitcnt lgkmcnt(5)
	v_mfma_f32_32x32x16_bf16 v[64:79], v[240:243], v[88:91], v[64:79]
	ds_read_b128 v[240:243], v252 offset:6784
	s_waitcnt lgkmcnt(5)
	v_mfma_f32_32x32x16_bf16 v[48:63], v[244:247], v[92:95], v[48:63]
	ds_read_b128 v[244:247], v252 offset:160
	s_waitcnt lgkmcnt(5)
	v_mfma_f32_32x32x16_bf16 v[64:79], v[248:251], v[92:95], v[64:79]
	ds_read_b128 v[248:251], v252 offset:6816
	s_waitcnt lgkmcnt(5)
	v_mfma_f32_32x32x16_bf16 v[48:63], v[176:179], v[96:99], v[48:63]
	ds_read_b128 v[176:179], v252 offset:13312
	s_waitcnt lgkmcnt(5)
	v_mfma_f32_32x32x16_bf16 v[64:79], v[232:235], v[96:99], v[64:79]
	ds_read_b128 v[232:235], v252 offset:19968
	s_waitcnt lgkmcnt(5)
	v_mfma_f32_32x32x16_bf16 v[48:63], v[236:239], v[100:103], v[48:63]
	ds_read_b128 v[236:239], v252 offset:13344
	s_waitcnt lgkmcnt(5)
	v_mfma_f32_32x32x16_bf16 v[64:79], v[240:243], v[100:103], v[64:79]
	ds_read_b128 v[240:243], v252 offset:20000
	s_waitcnt lgkmcnt(5)
	v_mfma_f32_32x32x16_bf16 v[48:63], v[244:247], v[112:115], v[48:63]
	ds_read_b128 v[244:247], v252 offset:13376
	s_waitcnt lgkmcnt(5)
	v_mfma_f32_32x32x16_bf16 v[64:79], v[248:251], v[112:115], v[64:79]
	ds_read_b128 v[248:251], v252 offset:20032
	s_waitcnt lgkmcnt(5)
	v_mfma_f32_32x32x16_bf16 v[144:159], v[176:179], v[80:83], v[0:15]
	ds_read_b128 v[176:179], v252 offset:13408
	s_waitcnt lgkmcnt(5)
	v_mfma_f32_32x32x16_bf16 v[160:175], v[232:235], v[80:83], v[0:15]
	ds_read_b128 v[232:235], v252 offset:20064
	s_nop 4
	v_exp_f32_e32 v48, v48
	v_exp_f32_e32 v49, v49
	v_exp_f32_e32 v50, v50
	s_waitcnt lgkmcnt(5)
	v_mfma_f32_32x32x16_bf16 v[144:159], v[236:239], v[88:91], v[144:159]
	ds_read_b128 v[236:239], v252 offset:13440
	v_exp_f32_e32 v51, v51
	v_exp_f32_e32 v52, v52
	v_exp_f32_e32 v53, v53
	s_waitcnt lgkmcnt(5)
	v_mfma_f32_32x32x16_bf16 v[160:175], v[240:243], v[88:91], v[160:175]
	ds_read_b128 v[240:243], v252 offset:20096
	v_exp_f32_e32 v54, v54
	v_exp_f32_e32 v55, v55
	v_exp_f32_e32 v56, v56
	s_waitcnt lgkmcnt(5)
	v_mfma_f32_32x32x16_bf16 v[144:159], v[244:247], v[92:95], v[144:159]
	ds_read_b128 v[244:247], v252 offset:13472
	v_exp_f32_e32 v57, v57
	v_exp_f32_e32 v58, v58
	v_exp_f32_e32 v59, v59
	s_waitcnt lgkmcnt(5)
	v_mfma_f32_32x32x16_bf16 v[160:175], v[248:251], v[92:95], v[160:175]
	ds_read_b128 v[248:251], v252 offset:20128
	v_exp_f32_e32 v60, v60
	v_exp_f32_e32 v61, v61
	v_exp_f32_e32 v62, v62
	s_waitcnt lgkmcnt(5)
	v_mfma_f32_32x32x16_bf16 v[144:159], v[176:179], v[96:99], v[144:159]
	ds_read_b64_tr_b16 v[176:177], v231 offset:53248
	ds_read_b64_tr_b16 v[178:179], v231 offset:54400
	v_exp_f32_e32 v63, v63
	v_exp_f32_e32 v64, v64
	v_exp_f32_e32 v65, v65
	s_waitcnt lgkmcnt(6)
	v_mfma_f32_32x32x16_bf16 v[160:175], v[232:235], v[96:99], v[160:175]
	ds_read_b64_tr_b16 v[232:233], v231 offset:53312
	ds_read_b64_tr_b16 v[234:235], v231 offset:54464
	v_exp_f32_e32 v66, v66
	v_exp_f32_e32 v67, v67
	v_exp_f32_e32 v68, v68
	s_waitcnt lgkmcnt(7)
	v_mfma_f32_32x32x16_bf16 v[144:159], v[236:239], v[100:103], v[144:159]
	ds_read_b64_tr_b16 v[236:237], v231 offset:55552
	ds_read_b64_tr_b16 v[238:239], v231 offset:56704
	v_exp_f32_e32 v69, v69
	v_exp_f32_e32 v70, v70
	v_exp_f32_e32 v71, v71
	s_waitcnt lgkmcnt(8)
	v_mfma_f32_32x32x16_bf16 v[160:175], v[240:243], v[100:103], v[160:175]
	ds_read_b64_tr_b16 v[240:241], v231 offset:55616
	ds_read_b64_tr_b16 v[242:243], v231 offset:56768
	v_exp_f32_e32 v72, v72
	v_exp_f32_e32 v73, v73
	v_exp_f32_e32 v74, v74
	s_waitcnt lgkmcnt(9)
	v_mfma_f32_32x32x16_bf16 v[144:159], v[244:247], v[112:115], v[144:159]
	v_cvt_pk_bf16_f32 v244, v48, v49
	v_cvt_pk_bf16_f32 v245, v50, v51
	v_cvt_pk_bf16_f32 v246, v52, v53
	v_cvt_pk_bf16_f32 v247, v54, v55
	v_exp_f32_e32 v75, v75
	s_waitcnt lgkmcnt(8)
	v_mfma_f32_32x32x16_bf16 v[160:175], v[248:251], v[112:115], v[160:175]
	v_exp_f32_e32 v76, v76
	v_exp_f32_e32 v77, v77
	v_exp_f32_e32 v78, v78
	s_waitcnt lgkmcnt(6)
	v_mfma_f32_32x32x16_bf16 v[16:31], v[244:247], v[176:179], v[16:31]
	ds_read_b64_tr_b16 v[176:177], v231 offset:57856
	ds_read_b64_tr_b16 v[178:179], v231 offset:59008
	v_cvt_pk_bf16_f32 v248, v56, v57
	v_cvt_pk_bf16_f32 v249, v58, v59
	v_cvt_pk_bf16_f32 v250, v60, v61
	v_cvt_pk_bf16_f32 v251, v62, v63
	v_exp_f32_e32 v79, v79
	v_exp_f32_e32 v144, v144
	s_waitcnt lgkmcnt(6)
	v_mfma_f32_32x32x16_bf16 v[32:47], v[244:247], v[232:235], v[32:47]
	ds_read_b64_tr_b16 v[232:233], v231 offset:57920
	ds_read_b64_tr_b16 v[234:235], v231 offset:59072
	v_cvt_pk_bf16_f32 v244, v64, v65
	v_cvt_pk_bf16_f32 v245, v66, v67
	v_cvt_pk_bf16_f32 v246, v68, v69
	v_cvt_pk_bf16_f32 v247, v70, v71
	v_exp_f32_e32 v145, v145
	v_exp_f32_e32 v146, v146
	s_waitcnt lgkmcnt(6)
	v_mfma_f32_32x32x16_bf16 v[16:31], v[248:251], v[236:239], v[16:31]
	ds_read_b64_tr_b16 v[236:237], v231 offset:60160
	ds_read_b64_tr_b16 v[238:239], v231 offset:61312
	v_exp_f32_e32 v147, v147
	v_exp_f32_e32 v148, v148
	v_exp_f32_e32 v149, v149
	v_exp_f32_e32 v150, v150
	s_waitcnt lgkmcnt(6)
	v_mfma_f32_32x32x16_bf16 v[32:47], v[248:251], v[240:243], v[32:47]
	ds_read_b64_tr_b16 v[240:241], v231 offset:60224
	ds_read_b64_tr_b16 v[242:243], v231 offset:61376
	v_cvt_pk_bf16_f32 v248, v72, v73
	v_cvt_pk_bf16_f32 v249, v74, v75
	v_cvt_pk_bf16_f32 v250, v76, v77
	v_cvt_pk_bf16_f32 v251, v78, v79
	v_exp_f32_e32 v151, v151
	v_exp_f32_e32 v152, v152
	s_waitcnt lgkmcnt(6)
	v_mfma_f32_32x32x16_bf16 v[16:31], v[244:247], v[176:179], v[16:31]
	ds_read_b64_tr_b16 v[176:177], v253 offset:53248
	ds_read_b64_tr_b16 v[178:179], v253 offset:54400
	v_exp_f32_e32 v153, v153
	v_exp_f32_e32 v154, v154
	v_exp_f32_e32 v155, v155
	v_exp_f32_e32 v156, v156
	s_waitcnt lgkmcnt(6)
	v_mfma_f32_32x32x16_bf16 v[32:47], v[244:247], v[232:235], v[32:47]
	ds_read_b64_tr_b16 v[232:233], v253 offset:53312
	ds_read_b64_tr_b16 v[234:235], v253 offset:54464
	v_cvt_pk_bf16_f32 v244, v144, v145
	v_cvt_pk_bf16_f32 v245, v146, v147
	v_cvt_pk_bf16_f32 v246, v148, v149
	v_cvt_pk_bf16_f32 v247, v150, v151
	v_exp_f32_e32 v157, v157
	v_exp_f32_e32 v158, v158
	s_waitcnt lgkmcnt(6)
	v_mfma_f32_32x32x16_bf16 v[16:31], v[248:251], v[236:239], v[16:31]
	ds_read_b64_tr_b16 v[236:237], v253 offset:55552
	ds_read_b64_tr_b16 v[238:239], v253 offset:56704
	v_exp_f32_e32 v159, v159
	v_exp_f32_e32 v160, v160
	v_exp_f32_e32 v161, v161
	v_exp_f32_e32 v162, v162
	s_waitcnt lgkmcnt(6)
	v_mfma_f32_32x32x16_bf16 v[32:47], v[248:251], v[240:243], v[32:47]
	ds_read_b64_tr_b16 v[240:241], v253 offset:55616
	ds_read_b64_tr_b16 v[242:243], v253 offset:56768
	v_cvt_pk_bf16_f32 v248, v152, v153
	v_cvt_pk_bf16_f32 v249, v154, v155
	v_cvt_pk_bf16_f32 v250, v156, v157
	v_cvt_pk_bf16_f32 v251, v158, v159
	v_exp_f32_e32 v163, v163
	v_exp_f32_e32 v164, v164
	s_waitcnt lgkmcnt(6)
	v_mfma_f32_32x32x16_bf16 v[16:31], v[244:247], v[176:179], v[16:31]
	ds_read_b64_tr_b16 v[176:177], v253 offset:57856
	ds_read_b64_tr_b16 v[178:179], v253 offset:59008
	v_exp_f32_e32 v165, v165
	v_exp_f32_e32 v166, v166
	v_exp_f32_e32 v167, v167
	v_exp_f32_e32 v168, v168
	s_waitcnt lgkmcnt(6)
	v_mfma_f32_32x32x16_bf16 v[32:47], v[244:247], v[232:235], v[32:47]
	ds_read_b64_tr_b16 v[232:233], v253 offset:57920
	ds_read_b64_tr_b16 v[234:235], v253 offset:59072
	v_cvt_pk_bf16_f32 v244, v160, v161
	v_cvt_pk_bf16_f32 v245, v162, v163
	v_cvt_pk_bf16_f32 v246, v164, v165
	v_cvt_pk_bf16_f32 v247, v166, v167
	v_exp_f32_e32 v169, v169
	v_exp_f32_e32 v170, v170
	s_waitcnt lgkmcnt(6)
	v_mfma_f32_32x32x16_bf16 v[16:31], v[248:251], v[236:239], v[16:31]
	ds_read_b64_tr_b16 v[236:237], v253 offset:60160
	ds_read_b64_tr_b16 v[238:239], v253 offset:61312
	v_exp_f32_e32 v171, v171
	v_exp_f32_e32 v172, v172
	v_exp_f32_e32 v173, v173
	v_exp_f32_e32 v174, v174
	s_waitcnt lgkmcnt(6)
	v_mfma_f32_32x32x16_bf16 v[32:47], v[248:251], v[240:243], v[32:47]
	ds_read_b64_tr_b16 v[240:241], v253 offset:60224
	ds_read_b64_tr_b16 v[242:243], v253 offset:61376
	v_exp_f32_e32 v175, v175
	v_cvt_pk_bf16_f32 v248, v168, v169
	v_cvt_pk_bf16_f32 v249, v170, v171
	v_cvt_pk_bf16_f32 v250, v172, v173
	v_cvt_pk_bf16_f32 v251, v174, v175
	v_add_f32_e32 v252, v48, v64
	v_add_f32_e32 v252, v252, v49
	s_waitcnt lgkmcnt(6)
	v_mfma_f32_32x32x16_bf16 v[16:31], v[244:247], v[176:179], v[16:31]
	v_add_f32_e32 v252, v252, v65
	v_add_f32_e32 v252, v252, v50
	v_add_f32_e32 v252, v252, v66
	v_add_f32_e32 v252, v252, v51
	v_add_f32_e32 v252, v252, v67
	v_add_f32_e32 v252, v252, v52
	v_add_f32_e32 v252, v252, v68
	v_add_f32_e32 v252, v252, v53
	s_waitcnt lgkmcnt(4)
	v_mfma_f32_32x32x16_bf16 v[32:47], v[244:247], v[232:235], v[32:47]
	v_add_f32_e32 v252, v252, v69
	v_add_f32_e32 v252, v252, v54
	v_add_f32_e32 v252, v252, v70
	v_add_f32_e32 v252, v252, v55
	v_add_f32_e32 v252, v252, v71
	v_add_f32_e32 v252, v252, v56
	v_add_f32_e32 v252, v252, v72
	v_add_f32_e32 v252, v252, v57
	s_waitcnt lgkmcnt(2)
	v_mfma_f32_32x32x16_bf16 v[16:31], v[248:251], v[236:239], v[16:31]
	v_add_f32_e32 v252, v252, v73
	v_add_f32_e32 v252, v252, v58
	v_add_f32_e32 v252, v252, v74
	v_add_f32_e32 v252, v252, v59
	v_add_f32_e32 v252, v252, v75
	v_add_f32_e32 v252, v252, v60
	v_add_f32_e32 v252, v252, v76
	v_add_f32_e32 v252, v252, v61
	s_waitcnt lgkmcnt(0)
	v_mfma_f32_32x32x16_bf16 v[32:47], v[248:251], v[240:243], v[32:47]
	v_add_f32_e32 v252, v252, v77
	v_add_f32_e32 v252, v252, v62
	v_add_f32_e32 v252, v252, v78
	v_add_f32_e32 v252, v252, v63
	v_add_f32_e32 v252, v252, v79
	v_add_f32_e32 v252, v252, v144
	v_add_f32_e32 v252, v252, v160
	v_add_f32_e32 v252, v252, v145
	v_add_f32_e32 v252, v252, v161
	v_add_f32_e32 v252, v252, v146
	v_add_f32_e32 v252, v252, v162
	v_add_f32_e32 v252, v252, v147
	v_add_f32_e32 v252, v252, v163
	v_add_f32_e32 v252, v252, v148
	v_add_f32_e32 v252, v252, v164
	v_add_f32_e32 v252, v252, v149
	v_add_f32_e32 v252, v252, v165
	v_add_f32_e32 v252, v252, v150
	v_add_f32_e32 v252, v252, v166
	v_add_f32_e32 v252, v252, v151
	v_add_f32_e32 v252, v252, v167
	v_add_f32_e32 v252, v252, v152
	v_add_f32_e32 v252, v252, v168
	v_add_f32_e32 v252, v252, v153
	v_add_f32_e32 v252, v252, v169
	v_add_f32_e32 v252, v252, v154
	v_add_f32_e32 v252, v252, v170
	v_add_f32_e32 v252, v252, v155
	v_add_f32_e32 v252, v252, v171
	v_add_f32_e32 v252, v252, v156
	v_add_f32_e32 v252, v252, v172
	v_add_f32_e32 v252, v252, v157
	v_add_f32_e32 v252, v252, v173
	v_add_f32_e32 v252, v252, v158
	v_add_f32_e32 v252, v252, v174
	v_add_f32_e32 v252, v252, v159
	v_add_f32_e32 v252, v252, v175
	v_add_f32_e32 v229, v229, v252

.LBB0_1575:
	v_lshlrev_b32_e32 v144, 10, v142
	v_mov_b32_e32 v145, 0
	v_or_b32_e32 v146, 1, v142
	v_lshlrev_b32_e32 v146, 10, v146
	v_mov_b32_e32 v147, 0
	v_or_b32_e32 v148, 2, v142
	v_lshlrev_b32_e32 v148, 10, v148
	v_mov_b32_e32 v149, 0
	v_or_b32_e32 v150, 3, v142
	v_lshlrev_b32_e32 v150, 10, v150
	v_mov_b32_e32 v151, 0
	v_add_u32_e32 v152, 0x2000, v144
	v_mov_b32_e32 v153, 0
	v_add_u32_e32 v154, 0x2400, v144
	v_mov_b32_e32 v155, 0
	v_add_u32_e32 v156, 0x2800, v144
	v_mov_b32_e32 v157, 0
	v_add_u32_e32 v158, 0x2c00, v144
	v_mov_b32_e32 v159, 0
	v_add_u32_e32 v160, 0x4000, v144
	v_mov_b32_e32 v161, 0
	v_add_u32_e32 v162, 0x4400, v144
	v_mov_b32_e32 v163, 0
	v_add_u32_e32 v164, 0x4800, v144
	v_mov_b32_e32 v165, 0
	v_add_u32_e32 v166, 0x4c00, v144
	v_mov_b32_e32 v167, 0
	v_add_u32_e32 v168, 0x6000, v144
	v_mov_b32_e32 v169, 0
	v_add_u32_e32 v170, 0x6400, v144
	v_mov_b32_e32 v171, 0
	v_add_u32_e32 v172, 0x6800, v144
	v_mov_b32_e32 v173, 0
	v_add_u32_e32 v174, 0x6c00, v144
	v_mov_b32_e32 v175, 0
	ds_bpermute_b32 v48, v199, v229
	s_and_saveexec_b64 s[0:1], s[2:3]
	s_cbranch_execz .LBB0_1550
	s_waitcnt lgkmcnt(0)
	v_add_f32_e32 v48, v229, v48
	ds_write_b32 v206, v48
	s_branch .LBB0_1550
